# first layer-0 residual row phase: parameter set-up loop de-serialised too (34 loads in flight, one wait)
# speedup vs baseline: 1.0098x; 1.0002x over previous
; template <bool HAS_Y, bool WRITE_X, bool HAS_XN> ...
;     for (int idx = tid; idx < 5 * DM; idx += NTHR) { const int r = idx >> 10, c = idx & (DM - 1);
;         if (HAS_Y) PRM[idx] = mods_y[((size_t)r * 6 + gate_idx) * DM + c] * ngy[c];
;         if (HAS_XN) { PRM[5 * DM + idx] = ng2[c] * (1.0f + mods_n[((size_t)r * 6 + sc_idx) * DM + c]); PRM[10 * DM + idx] = mods_n[((size_t)r * 6 + sh_idx) * DM + c]; } }
;     __syncthreads();
;     ...
;     RowRegs A, B, C, D;
;     int row = gw;
;     if (row < MROWS) {
;         row_load<HAS_Y>(A, row, ROW_ON(row), lane, xin_lat, xin_ctx, Y); row_load<HAS_Y>(B, row + NGW, ROW_ON(row + NGW), lane, xin_lat, xin_ctx, Y);
; __global__ void __launch_bounds__(mk::NTHR, 2) fwd_kernel(Args args) {
;     ...
;     if (IN(7)) {
;         if (bx < 16) { pg8::Gemm g{MIX, W_ABOUT, MROWS, DM, DM}; pg8::CtxOrder S{bx}; pg8::EpiStoreBf16 E{Y, DM};
;             pg8::gemm_phase<pg8::EpiStoreBf16, pg8::CtxOrder, true, true>(ldsl, g, S, E); }
;         else row_phase<true, true, true>((bx - 16) * NWAVES + wave, (G - 16) * NWAVES, lane, tid, (float*)lds, 1, x, ctx, out, CTXS, Y, mods, 2, norm_g + 1 * DM, norm_g + 2 * DM, mods, 3, 4, XN);
.LBB0_614:
	s_cmp_lt_i32 s84, 8
	s_cselect_b64 s[4:5], -1, 0
	s_add_u32 s6, s90, 0x3400000
	s_addc_u32 s7, s91, 0
	s_and_b64 s[2:3], s[4:5], s[2:3]
	s_andn2_b64 vcc, exec, s[2:3]
	s_cbranch_vccnz .LBB0_826
	s_cmp_gt_i32 s93, 15
	s_mov_b64 s[4:5], -1
	s_cbranch_scc0 .LBB0_692
	s_add_u32 s4, s60, 0x1000
	s_addc_u32 s5, s61, 0
	s_add_u32 s8, s60, 0x2000
	s_addc_u32 s9, s61, 0
	s_waitcnt vmcnt(0)
	v_lshl_add_u32 v4, v0, 2, 0
	global_load_dword v8, v4, s[4:5]
	global_load_dword v9, v4, s[4:5] offset:2048
	global_load_dword v10, v4, s[8:9]
	global_load_dword v11, v4, s[8:9] offset:2048
	s_add_u32 s10, s94, 0x2000
	s_addc_u32 s11, s95, 0
	s_add_u32 s12, s94, 0x3000
	s_addc_u32 s13, s95, 0
	s_add_u32 s98, s94, 0x4000
	s_addc_u32 s99, s95, 0
	global_load_dword v12, v4, s[10:11]
	global_load_dword v13, v4, s[10:11] offset:2048
	global_load_dword v14, v4, s[12:13]
	global_load_dword v15, v4, s[12:13] offset:2048
	global_load_dword v16, v4, s[98:99]
	global_load_dword v17, v4, s[98:99] offset:2048
	s_add_u32 s10, s94, 0x8000
	s_addc_u32 s11, s95, 0
	s_add_u32 s12, s94, 0x9000
	s_addc_u32 s13, s95, 0
	s_add_u32 s98, s94, 0xa000
	s_addc_u32 s99, s95, 0
	global_load_dword v18, v4, s[10:11]
	global_load_dword v19, v4, s[10:11] offset:2048
	global_load_dword v20, v4, s[12:13]
	global_load_dword v21, v4, s[12:13] offset:2048
	global_load_dword v22, v4, s[98:99]
	global_load_dword v23, v4, s[98:99] offset:2048
	s_add_u32 s10, s94, 0xe000
	s_addc_u32 s11, s95, 0
	s_add_u32 s12, s94, 0xf000
	s_addc_u32 s13, s95, 0
	s_add_u32 s98, s94, 0x10000
	s_addc_u32 s99, s95, 0
	global_load_dword v24, v4, s[10:11]
	global_load_dword v25, v4, s[10:11] offset:2048
	global_load_dword v26, v4, s[12:13]
	global_load_dword v27, v4, s[12:13] offset:2048
	global_load_dword v28, v4, s[98:99]
	global_load_dword v29, v4, s[98:99] offset:2048
	s_add_u32 s10, s94, 0x14000
	s_addc_u32 s11, s95, 0
	s_add_u32 s12, s94, 0x15000
	s_addc_u32 s13, s95, 0
	s_add_u32 s98, s94, 0x16000
	s_addc_u32 s99, s95, 0
	global_load_dword v30, v4, s[10:11]
	global_load_dword v31, v4, s[10:11] offset:2048
	global_load_dword v32, v4, s[12:13]
	global_load_dword v33, v4, s[12:13] offset:2048
	global_load_dword v34, v4, s[98:99]
	global_load_dword v35, v4, s[98:99] offset:2048
	s_add_u32 s10, s94, 0x1a000
	s_addc_u32 s11, s95, 0
	s_add_u32 s12, s94, 0x1b000
	s_addc_u32 s13, s95, 0
	s_add_u32 s98, s94, 0x1c000
	s_addc_u32 s99, s95, 0
	global_load_dword v36, v4, s[10:11]
	global_load_dword v37, v4, s[10:11] offset:2048
	global_load_dword v38, v4, s[12:13]
	global_load_dword v39, v4, s[12:13] offset:2048
	global_load_dword v40, v4, s[98:99]
	global_load_dword v41, v4, s[98:99] offset:2048
	s_waitcnt vmcnt(0)
	v_mul_f32_e32 v12, v12, v8
	v_add_f32_e32 v16, 1.0, v16
	v_mul_f32_e32 v16, v10, v16
	ds_write_b32 v4, v14 offset:40960
	ds_write2st64_b32 v4, v12, v16 offset0:0 offset1:80
	v_mul_f32_e32 v13, v13, v9
	v_add_f32_e32 v17, 1.0, v17
	v_mul_f32_e32 v17, v11, v17
	ds_write_b32 v4, v15 offset:43008
	ds_write2st64_b32 v4, v13, v17 offset0:8 offset1:88
	v_mul_f32_e32 v18, v18, v8
	v_add_f32_e32 v22, 1.0, v22
	v_mul_f32_e32 v22, v10, v22
	ds_write_b32 v4, v20 offset:45056
	ds_write2st64_b32 v4, v18, v22 offset0:16 offset1:96
	v_mul_f32_e32 v19, v19, v9
	v_add_f32_e32 v23, 1.0, v23
	v_mul_f32_e32 v23, v11, v23
	ds_write_b32 v4, v21 offset:47104
	ds_write2st64_b32 v4, v19, v23 offset0:24 offset1:104
	v_mul_f32_e32 v24, v24, v8
	v_add_f32_e32 v28, 1.0, v28
	v_mul_f32_e32 v28, v10, v28
	ds_write_b32 v4, v26 offset:49152
	ds_write2st64_b32 v4, v24, v28 offset0:32 offset1:112
	v_mul_f32_e32 v25, v25, v9
	v_add_f32_e32 v29, 1.0, v29
	v_mul_f32_e32 v29, v11, v29
	ds_write_b32 v4, v27 offset:51200
	ds_write2st64_b32 v4, v25, v29 offset0:40 offset1:120
	v_mul_f32_e32 v30, v30, v8
	v_add_f32_e32 v34, 1.0, v34
	v_mul_f32_e32 v34, v10, v34
	ds_write_b32 v4, v32 offset:53248
	ds_write2st64_b32 v4, v30, v34 offset0:48 offset1:128
	v_mul_f32_e32 v31, v31, v9
	v_add_f32_e32 v35, 1.0, v35
	v_mul_f32_e32 v35, v11, v35
	ds_write_b32 v4, v33 offset:55296
	ds_write2st64_b32 v4, v31, v35 offset0:56 offset1:136
	v_mul_f32_e32 v36, v36, v8
	v_add_f32_e32 v40, 1.0, v40
	v_mul_f32_e32 v40, v10, v40
	ds_write_b32 v4, v38 offset:57344
	ds_write2st64_b32 v4, v36, v40 offset0:64 offset1:144
	v_mul_f32_e32 v37, v37, v9
	v_add_f32_e32 v41, 1.0, v41
	v_mul_f32_e32 v41, v11, v41
	ds_write_b32 v4, v39 offset:59392
	ds_write2st64_b32 v4, v37, v41 offset0:72 offset1:152
	s_lshl_b32 s4, s93, 3
	v_readlane_b32 s5, v255, 8
	s_add_i32 s22, s4, s5
	s_add_i32 s4, s22, 0xffffff80
	s_cmp_lt_i32 s4, 0x8400
	s_waitcnt lgkmcnt(0)
	s_barrier
	s_cbranch_scc0 .LBB0_691
	s_mul_hi_i32 s5, s4, 0x3e0f83e1
	s_lshr_b32 s8, s5, 31
	s_ashr_i32 s5, s5, 11
	s_add_i32 s5, s5, s8
	s_mul_i32 s8, s5, 0x2100
	s_sub_i32 s8, s4, s8
	s_cmpk_gt_i32 s8, 0x1fff
	s_cbranch_scc1 .LBB0_622
	s_mul_i32 s11, s5, 0xffffdf00
	s_add_i32 s11, s11, s4
	s_cmpk_lt_i32 s11, 0x2000
	s_cbranch_scc0 .LBB0_623
	s_lshl_b32 s8, s5, 13
	s_add_i32 s10, s11, s8
	s_mov_b64 s[12:13], 0
	s_mov_b64 s[8:9], s[48:49]
	s_branch .LBB0_624

; __global__ void __launch_bounds__(mk::NTHR, 2) fwd_kernel(Args args) {
;     ...
;     if (IN(13)) {
;         for (int u = vcu; u < 1024; u += G) { const int qb = u & 31, gq = (u >> 5) & 3, kvh = (u >> 7) & 1, b = u >> 8, h = kvh * 4 + gq;
.LBB0_1582:
	s_nop 0
	s_nop 0
	s_nop 0
	s_nop 0
	s_nop 0
	s_nop 0
	s_nop 0
	s_nop 0
	s_nop 0
	s_nop 0
	s_nop 0
	s_nop 0
	s_nop 0
	s_nop 0
	s_nop 0
	s_nop 0
	s_nop 0
	s_nop 0
	s_nop 0
	s_nop 0
	s_nop 0
	s_cmp_lt_i32 s84, 14
	s_cselect_b64 s[4:5], -1, 0
	s_and_b64 s[28:29], s[4:5], s[2:3]
	s_xor_b64 s[2:3], s[28:29], -1
	s_cmpk_gt_i32 s33, 0x3ff
	s_cselect_b64 s[4:5], -1, 0
	s_or_b64 s[2:3], s[2:3], s[4:5]
	s_and_b64 vcc, exec, s[2:3]
	s_cbranch_vccnz .LBB0_1602
	v_readfirstlane_b32 s98, v0
	s_bitcmp1_b32 s98, 8
	s_cbranch_scc0 .Lattn_noprio
	s_setprio 1
